# adds: F1 merge-GEMM K-loop LDS fragment reads pipelined (second fragment set in free VGPRs); GQA tile loads no longer drained before the tile compute
# speedup vs baseline: 1.0185x; 1.0036x over previous
.LBB0_168:
	s_add_i32 s4, s17, 0
	s_add_i32 s5, s4, s14
	v_add_u32_e32 v206, s5, v194
	v_add_u32_e32 v215, v206, v188
	v_add_u32_e32 v228, s4, v193
	v_add_u32_e32 v229, v228, v188
	ds_read_b128 v[200:203], v229
	ds_read_b128 v[196:199], v215 offset:32768
	ds_read_b128 v[216:219], v215 offset:34816
	ds_read_b128 v[220:223], v215 offset:36864
	ds_read_b128 v[224:227], v215 offset:38912
	ds_read_b128 v[246:249], v229 offset:2048
	v_add_u32_e32 v206, v206, v195
	v_add_u32_e32 v228, v228, v195
	s_waitcnt lgkmcnt(4)
	v_mfma_f32_16x16x32_bf16 v[60:63], v[196:199], v[200:203], v[60:63]
	s_waitcnt lgkmcnt(3)
	v_mfma_f32_16x16x32_bf16 v[56:59], v[216:219], v[200:203], v[56:59]
	s_waitcnt lgkmcnt(2)
	v_mfma_f32_16x16x32_bf16 v[52:55], v[220:223], v[200:203], v[52:55]
	s_waitcnt lgkmcnt(1)
	v_mfma_f32_16x16x32_bf16 v[48:51], v[224:227], v[200:203], v[48:51]
	ds_read_b128 v[200:203], v229 offset:4096
	ds_read_b128 v[230:233], v206 offset:32768
	ds_read_b128 v[234:237], v206 offset:34816
	s_waitcnt lgkmcnt(3)
	v_mfma_f32_16x16x32_bf16 v[44:47], v[196:199], v[246:249], v[44:47]
	v_mfma_f32_16x16x32_bf16 v[40:43], v[216:219], v[246:249], v[40:43]
	v_mfma_f32_16x16x32_bf16 v[36:39], v[220:223], v[246:249], v[36:39]
	v_mfma_f32_16x16x32_bf16 v[32:35], v[224:227], v[246:249], v[32:35]
	ds_read_b128 v[246:249], v229 offset:6144
	ds_read_b128 v[238:241], v206 offset:36864
	ds_read_b128 v[242:245], v206 offset:38912
	s_waitcnt lgkmcnt(5)
	v_mfma_f32_16x16x32_bf16 v[28:31], v[196:199], v[200:203], v[28:31]
	v_mfma_f32_16x16x32_bf16 v[24:27], v[216:219], v[200:203], v[24:27]
	v_mfma_f32_16x16x32_bf16 v[20:23], v[220:223], v[200:203], v[20:23]
	v_mfma_f32_16x16x32_bf16 v[16:19], v[224:227], v[200:203], v[16:19]
	ds_read_b128 v[200:203], v228
	s_waitcnt lgkmcnt(3)
	v_mfma_f32_16x16x32_bf16 v[12:15], v[196:199], v[246:249], v[12:15]
	v_mfma_f32_16x16x32_bf16 v[8:11], v[216:219], v[246:249], v[8:11]
	v_mfma_f32_16x16x32_bf16 v[4:7], v[220:223], v[246:249], v[4:7]
	v_mfma_f32_16x16x32_bf16 v[0:3], v[224:227], v[246:249], v[0:3]
	ds_read_b128 v[246:249], v228 offset:2048
	s_waitcnt lgkmcnt(1)
	v_mfma_f32_16x16x32_bf16 v[60:63], v[230:233], v[200:203], v[60:63]
	v_mfma_f32_16x16x32_bf16 v[56:59], v[234:237], v[200:203], v[56:59]
	v_mfma_f32_16x16x32_bf16 v[52:55], v[238:241], v[200:203], v[52:55]
	v_mfma_f32_16x16x32_bf16 v[48:51], v[242:245], v[200:203], v[48:51]
	ds_read_b128 v[200:203], v228 offset:4096
	s_waitcnt lgkmcnt(1)
	v_mfma_f32_16x16x32_bf16 v[44:47], v[230:233], v[246:249], v[44:47]
	v_mfma_f32_16x16x32_bf16 v[40:43], v[234:237], v[246:249], v[40:43]
	v_mfma_f32_16x16x32_bf16 v[36:39], v[238:241], v[246:249], v[36:39]
	v_mfma_f32_16x16x32_bf16 v[32:35], v[242:245], v[246:249], v[32:35]
	ds_read_b128 v[246:249], v228 offset:6144
	s_waitcnt lgkmcnt(1)
	v_mfma_f32_16x16x32_bf16 v[28:31], v[230:233], v[200:203], v[28:31]
	v_mfma_f32_16x16x32_bf16 v[24:27], v[234:237], v[200:203], v[24:27]
	v_mfma_f32_16x16x32_bf16 v[20:23], v[238:241], v[200:203], v[20:23]
	v_mfma_f32_16x16x32_bf16 v[16:19], v[242:245], v[200:203], v[16:19]
	s_waitcnt lgkmcnt(0)
	v_mfma_f32_16x16x32_bf16 v[12:15], v[230:233], v[246:249], v[12:15]
	v_mfma_f32_16x16x32_bf16 v[8:11], v[234:237], v[246:249], v[8:11]
	v_mfma_f32_16x16x32_bf16 v[4:7], v[238:241], v[246:249], v[4:7]
	v_mfma_f32_16x16x32_bf16 v[0:3], v[242:245], v[246:249], v[0:3]
	s_mov_b64 s[4:5], -1
	s_and_b64 vcc, exec, s[2:3]
	s_cbranch_vccz .LBB0_170
	s_waitcnt vmcnt(0)
	s_waitcnt lgkmcnt(0)
	s_barrier
	s_mov_b64 s[4:5], 0

.LBB0_233:
	s_or_b64 exec, exec, s[6:7]
	s_branch .LBB0_235

.LBB0_235:
	s_add_i32 s6, s73, s85
	s_add_i32 s0, s6, 0xffffff40
	s_cmpk_gt_u32 s0, 0x1fff
	s_cbranch_scc1 .LBB0_243
	s_addk_i32 s6, 0xff7f
	v_cmp_ge_i32_e32 vcc, s6, v195
	v_cmp_le_i32_e64 s[6:7], s0, v196
	s_and_b64 s[6:7], vcc, s[6:7]
	s_and_saveexec_b64 s[76:77], s[6:7]
	s_cbranch_execz .LBB0_242
	s_bitcmp1_b32 s75, 0
	s_cselect_b32 s0, 0x4900, 0
	s_add_i32 s0, s0, 0
	v_add_u32_e32 v216, s0, v188
	v_add_u32_e32 v184, v216, v197
	ds_read_b128 v[64:67], v184 offset:4608
	ds_read_b128 v[68:71], v184
	ds_read_b128 v[218:221], v184 offset:32
	ds_read_b128 v[222:225], v184 offset:4640
	v_cvt_f32_i32_e32 v215, v200
	s_waitcnt lgkmcnt(3)
	v_mfma_f32_32x32x16_bf16 v[96:111], v[64:67], v[128:131], 0
	s_mov_b32 s0, 0xff800000
	v_add_f32_e32 v217, -1.0, v215
	v_cmp_le_f32_e64 s[8:9], |v217|, s78
	v_add_f32_e32 v217, -2.0, v215
	v_cmp_le_f32_e64 s[10:11], |v217|, s78
	v_add_f32_e32 v217, 0xc0400000, v215
	s_waitcnt lgkmcnt(2)
	v_mfma_f32_32x32x16_bf16 v[112:127], v[68:71], v[128:131], 0
	v_cmp_le_f32_e64 s[12:13], |v217|, s78
	v_cmp_le_f32_e64 s[6:7], |v215|, s78
	v_mfma_f32_32x32x16_bf16 v[80:95], v[68:71], v[136:139], 0
	v_mfma_f32_32x32x16_bf16 v[64:79], v[64:67], v[136:139], 0
	s_waitcnt lgkmcnt(1)
	v_mfma_f32_32x32x16_bf16 v[112:127], v[218:221], v[132:135], v[112:127]
	v_mfma_f32_32x32x16_bf16 v[80:95], v[218:221], v[140:143], v[80:95]
	s_waitcnt lgkmcnt(0)
	v_mfma_f32_32x32x16_bf16 v[96:111], v[222:225], v[132:135], v[96:111]
	v_mfma_f32_32x32x16_bf16 v[64:79], v[222:225], v[140:143], v[64:79]
	ds_read_b128 v[218:221], v184 offset:64
	ds_read_b128 v[222:225], v184 offset:4672
	s_waitcnt lgkmcnt(1)
	v_mfma_f32_32x32x16_bf16 v[112:127], v[218:221], v[144:147], v[112:127]
	v_mfma_f32_32x32x16_bf16 v[80:95], v[218:221], v[152:155], v[80:95]
	s_waitcnt lgkmcnt(0)
	v_mfma_f32_32x32x16_bf16 v[96:111], v[222:225], v[144:147], v[96:111]
	v_mfma_f32_32x32x16_bf16 v[64:79], v[222:225], v[152:155], v[64:79]
	ds_read_b128 v[218:221], v184 offset:96
	ds_read_b128 v[222:225], v184 offset:4704
	s_waitcnt lgkmcnt(1)
	v_mfma_f32_32x32x16_bf16 v[112:127], v[218:221], v[148:151], v[112:127]
	v_mfma_f32_32x32x16_bf16 v[80:95], v[218:221], v[156:159], v[80:95]
	s_nop 10
	v_mul_f32_e32 v112, 0x3e38aa3b, v112
	v_mul_f32_e32 v113, 0x3e38aa3b, v113
	v_mul_f32_e32 v114, 0x3e38aa3b, v114
	v_mul_f32_e32 v115, 0x3e38aa3b, v115
	v_mul_f32_e32 v116, 0x3e38aa3b, v116
	v_mul_f32_e32 v117, 0x3e38aa3b, v117
	v_mul_f32_e32 v118, 0x3e38aa3b, v118
	s_waitcnt lgkmcnt(0)
	v_mfma_f32_32x32x16_bf16 v[96:111], v[222:225], v[148:151], v[96:111]
	v_mul_f32_e32 v119, 0x3e38aa3b, v119
	v_mul_f32_e32 v120, 0x3e38aa3b, v120
	v_mul_f32_e32 v121, 0x3e38aa3b, v121
	v_mul_f32_e32 v122, 0x3e38aa3b, v122
	v_mul_f32_e32 v123, 0x3e38aa3b, v123
	v_mul_f32_e32 v124, 0x3e38aa3b, v124
	v_mul_f32_e32 v125, 0x3e38aa3b, v125
	v_mfma_f32_32x32x16_bf16 v[64:79], v[222:225], v[156:159], v[64:79]
	ds_read_b128 v[218:221], v216 offset:18432
	ds_read_b128 v[222:225], v216 offset:18464
	ds_read_b128 v[226:229], v216 offset:18528
	ds_read_b128 v[230:233], v216 offset:18560
	ds_read_b128 v[234:237], v216 offset:18592
	s_waitcnt lgkmcnt(4)
	v_cvt_f32_i32_e32 v185, v218
	v_cvt_f32_i32_e32 v201, v219
	v_cvt_f32_i32_e32 v202, v220
	s_waitcnt lgkmcnt(3)
	v_cvt_f32_i32_e32 v217, v222
	v_cvt_f32_i32_e32 v218, v223
	v_cvt_f32_i32_e32 v219, v224
	v_cvt_f32_i32_e32 v220, v225
	ds_read_b128 v[222:225], v216 offset:18496
	v_cvt_f32_i32_e32 v203, v221
	v_add_f32_e32 v221, 0xc1000000, v215
	v_cmp_le_f32_e64 s[14:15], |v221|, s78
	v_add_f32_e32 v221, 0xc1100000, v215
	v_cmp_le_f32_e64 s[16:17], |v221|, s78
	v_add_f32_e32 v221, 0xc1200000, v215
	v_cmp_le_f32_e64 s[18:19], |v221|, s78
	v_add_f32_e32 v221, 0xc1300000, v215
	v_cmp_le_f32_e64 s[20:21], |v221|, s78
	s_waitcnt lgkmcnt(0)
	v_cvt_f32_i32_e32 v221, v222
	v_cvt_f32_i32_e32 v222, v223
	v_cvt_f32_i32_e32 v223, v224
	v_cvt_f32_i32_e32 v224, v225
	v_add_f32_e32 v225, 0xc1800000, v215
	v_cmp_le_f32_e64 s[22:23], |v225|, s78
	v_add_f32_e32 v225, 0xc1880000, v215
	v_cmp_le_f32_e64 s[24:25], |v225|, s78
	v_add_f32_e32 v225, 0xc1900000, v215
	v_cmp_le_f32_e64 s[26:27], |v225|, s78
	v_add_f32_e32 v225, 0xc1980000, v215
	v_cmp_le_f32_e64 s[28:29], |v225|, s78
	v_cvt_f32_i32_e32 v225, v226
	v_cvt_f32_i32_e32 v226, v227
	v_cvt_f32_i32_e32 v227, v228
	v_cvt_f32_i32_e32 v228, v229
	v_add_f32_e32 v229, 0xc1c00000, v215
	v_cmp_le_f32_e64 s[30:31], |v229|, s78
	v_add_f32_e32 v229, 0xc1c80000, v215
	v_cmp_le_f32_e64 s[34:35], |v229|, s78
	v_add_f32_e32 v229, 0xc1d00000, v215
	v_cmp_le_f32_e64 s[36:37], |v229|, s78
	v_add_f32_e32 v229, 0xc1d80000, v215
	v_cmp_le_f32_e64 s[38:39], |v229|, s78
	v_cvt_f32_i32_e32 v229, v230
	v_cvt_f32_i32_e32 v230, v231
	v_cvt_f32_i32_e32 v231, v232
	v_cvt_f32_i32_e32 v232, v233
	v_add_f32_e32 v233, 0xc2000000, v215
	v_cmp_le_f32_e64 s[40:41], |v233|, s78
	v_add_f32_e32 v233, 0xc2040000, v215
	v_cmp_le_f32_e64 s[42:43], |v233|, s78
	v_add_f32_e32 v233, 0xc2080000, v215
	v_cmp_le_f32_e64 s[44:45], |v233|, s78
	v_add_f32_e32 v233, 0xc20c0000, v215
	ds_read_b128 v[238:241], v216 offset:18624
	ds_read_b128 v[242:245], v216 offset:18656
	v_cmp_le_f32_e64 s[46:47], |v233|, s78
	v_cvt_f32_i32_e32 v233, v234
	v_cvt_f32_i32_e32 v234, v235
	v_cvt_f32_i32_e32 v235, v236
	v_cvt_f32_i32_e32 v236, v237
	v_add_f32_e32 v237, 0xc2200000, v215
	v_cmp_le_f32_e64 s[48:49], |v237|, s78
	v_add_f32_e32 v237, 0xc2240000, v215
	v_cmp_le_f32_e64 s[50:51], |v237|, s78
	v_add_f32_e32 v237, 0xc2280000, v215
	v_cmp_le_f32_e64 s[52:53], |v237|, s78
	v_add_f32_e32 v237, 0xc22c0000, v215
	v_cmp_le_f32_e64 s[54:55], |v237|, s78
	s_waitcnt lgkmcnt(1)
	v_cvt_f32_i32_e32 v237, v238
	v_cvt_f32_i32_e32 v238, v239
	v_cvt_f32_i32_e32 v239, v240
	v_cvt_f32_i32_e32 v240, v241
	v_add_f32_e32 v241, 0xc2400000, v215
	v_cmp_le_f32_e64 s[56:57], |v241|, s78
	v_add_f32_e32 v241, 0xc2440000, v215
	v_cmp_le_f32_e64 s[58:59], |v241|, s78
	v_add_f32_e32 v241, 0xc2480000, v215
	v_cmp_le_f32_e64 s[60:61], |v241|, s78
	v_add_f32_e32 v241, 0xc24c0000, v215
	v_cmp_le_f32_e64 s[62:63], |v241|, s78
	s_waitcnt lgkmcnt(0)
	v_cvt_f32_i32_e32 v241, v243
	v_sub_f32_e32 v185, v193, v185
	v_sub_f32_e32 v201, v193, v201
	v_cvt_f32_i32_e32 v216, v242
	v_add_f32_e32 v242, 0xc2600000, v215
	v_fma_f32 v112, v198, |v185|, v112
	v_fma_f32 v113, v198, |v201|, v113
	v_sub_f32_e32 v202, v193, v202
	v_sub_f32_e32 v203, v193, v203
	v_cmp_le_f32_e64 s[64:65], |v242|, s78
	v_sub_f32_e32 v242, v193, v241
	v_add_f32_e32 v241, 0xc2640000, v215
	v_cndmask_b32_e64 v112, v210, v112, s[6:7]
	v_cndmask_b32_e64 v113, v210, v113, s[8:9]
	v_fma_f32 v114, v198, |v202|, v114
	v_fma_f32 v115, v198, |v203|, v115
	v_sub_f32_e32 v217, v193, v217
	v_sub_f32_e32 v218, v193, v218
	v_cmp_le_f32_e64 s[66:67], |v241|, s78
	v_add_f32_e32 v241, 0xc2680000, v215
	v_add_f32_e32 v215, 0xc26c0000, v215
	v_cndmask_b32_e64 v114, v210, v114, s[10:11]
	v_cndmask_b32_e64 v115, v210, v115, s[12:13]
	v_fma_f32 v116, v198, |v217|, v116
	v_fma_f32 v117, v198, |v218|, v117
	v_sub_f32_e32 v219, v193, v219
	v_sub_f32_e32 v220, v193, v220
	v_cmp_le_f32_e64 s[70:71], |v215|, s78
	v_max3_f32 v215, v112, s0, v113
	v_cndmask_b32_e64 v116, v210, v116, s[14:15]
	v_cndmask_b32_e64 v117, v210, v117, s[16:17]
	v_fma_f32 v118, v198, |v219|, v118
	v_fma_f32 v119, v198, |v220|, v119
	v_sub_f32_e32 v221, v193, v221
	v_sub_f32_e32 v222, v193, v222
	v_max3_f32 v215, v215, v114, v115
	v_cndmask_b32_e64 v118, v210, v118, s[18:19]
	v_cndmask_b32_e64 v119, v210, v119, s[20:21]
	v_fma_f32 v120, v198, |v221|, v120
	v_fma_f32 v121, v198, |v222|, v121
	v_sub_f32_e32 v223, v193, v223
	v_sub_f32_e32 v224, v193, v224
	v_max3_f32 v215, v215, v116, v117
	v_cndmask_b32_e64 v120, v210, v120, s[22:23]
	v_cndmask_b32_e64 v121, v210, v121, s[24:25]
	v_fma_f32 v122, v198, |v223|, v122
	v_fma_f32 v123, v198, |v224|, v123
	v_sub_f32_e32 v225, v193, v225
	v_sub_f32_e32 v226, v193, v226
	v_max3_f32 v215, v215, v118, v119
	v_cndmask_b32_e64 v122, v210, v122, s[26:27]
	v_cndmask_b32_e64 v123, v210, v123, s[28:29]
	v_fma_f32 v124, v198, |v225|, v124
	v_fma_f32 v125, v198, |v226|, v125
	v_sub_f32_e32 v227, v193, v227
	v_mul_f32_e32 v126, 0x3e38aa3b, v126
	v_sub_f32_e32 v228, v193, v228
	v_mul_f32_e32 v127, 0x3e38aa3b, v127
	v_max3_f32 v215, v215, v120, v121
	v_cndmask_b32_e64 v124, v210, v124, s[30:31]
	v_cndmask_b32_e64 v125, v210, v125, s[34:35]
	v_fma_f32 v126, v198, |v227|, v126
	v_fma_f32 v127, v198, |v228|, v127
	v_sub_f32_e32 v229, v193, v229
	v_mul_f32_e32 v96, 0x3e38aa3b, v96
	v_sub_f32_e32 v230, v193, v230
	v_mul_f32_e32 v97, 0x3e38aa3b, v97
	v_max3_f32 v215, v215, v122, v123
	v_cndmask_b32_e64 v126, v210, v126, s[36:37]
	v_cndmask_b32_e64 v127, v210, v127, s[38:39]
	v_fma_f32 v96, v198, |v229|, v96
	v_fma_f32 v97, v198, |v230|, v97
	v_sub_f32_e32 v231, v193, v231
	v_mul_f32_e32 v98, 0x3e38aa3b, v98
	v_sub_f32_e32 v232, v193, v232
	v_mul_f32_e32 v99, 0x3e38aa3b, v99
	v_max3_f32 v215, v215, v124, v125
	v_cndmask_b32_e64 v96, v210, v96, s[40:41]
	v_cndmask_b32_e64 v97, v210, v97, s[42:43]
	v_fma_f32 v98, v198, |v231|, v98
	v_fma_f32 v99, v198, |v232|, v99
	v_sub_f32_e32 v233, v193, v233
	v_mul_f32_e32 v100, 0x3e38aa3b, v100
	v_sub_f32_e32 v234, v193, v234
	v_mul_f32_e32 v101, 0x3e38aa3b, v101
	v_max3_f32 v215, v215, v126, v127
	v_cndmask_b32_e64 v98, v210, v98, s[44:45]
	v_cndmask_b32_e64 v99, v210, v99, s[46:47]
	v_fma_f32 v100, v198, |v233|, v100
	v_fma_f32 v101, v198, |v234|, v101
	v_sub_f32_e32 v235, v193, v235
	v_mul_f32_e32 v102, 0x3e38aa3b, v102
	v_sub_f32_e32 v236, v193, v236
	v_mul_f32_e32 v103, 0x3e38aa3b, v103
	v_cvt_f32_i32_e32 v243, v244
	v_cvt_f32_i32_e32 v244, v245
	v_max3_f32 v215, v215, v96, v97
	v_cndmask_b32_e64 v100, v210, v100, s[48:49]
	v_cndmask_b32_e64 v101, v210, v101, s[50:51]
	v_fma_f32 v102, v198, |v235|, v102
	v_fma_f32 v103, v198, |v236|, v103
	v_sub_f32_e32 v237, v193, v237
	v_mul_f32_e32 v104, 0x3e38aa3b, v104
	v_sub_f32_e32 v238, v193, v238
	v_mul_f32_e32 v105, 0x3e38aa3b, v105
	v_max3_f32 v215, v215, v98, v99
	v_cndmask_b32_e64 v102, v210, v102, s[52:53]
	v_cndmask_b32_e64 v103, v210, v103, s[54:55]
	v_fma_f32 v104, v198, |v237|, v104
	v_fma_f32 v105, v198, |v238|, v105
	v_sub_f32_e32 v239, v193, v239
	v_mul_f32_e32 v106, 0x3e38aa3b, v106
	v_sub_f32_e32 v240, v193, v240
	v_mul_f32_e32 v107, 0x3e38aa3b, v107
	v_max3_f32 v215, v215, v100, v101
	v_cndmask_b32_e64 v104, v210, v104, s[56:57]
	v_cndmask_b32_e64 v105, v210, v105, s[58:59]
	v_fma_f32 v106, v198, |v239|, v106
	v_fma_f32 v107, v198, |v240|, v107
	v_sub_f32_e32 v216, v193, v216
	v_mul_f32_e32 v108, 0x3e38aa3b, v108
	v_mul_f32_e32 v109, 0x3e38aa3b, v109
	v_max3_f32 v215, v215, v102, v103
	v_and_b32_e32 v245, 64, v207
	v_cndmask_b32_e64 v106, v210, v106, s[60:61]
	v_cndmask_b32_e64 v107, v210, v107, s[62:63]
	v_fma_f32 v108, v198, |v216|, v108
	v_fma_f32 v109, v198, |v242|, v109
	v_sub_f32_e32 v243, v193, v243
	v_cmp_le_f32_e64 s[68:69], |v241|, s78
	v_mul_f32_e32 v110, 0x3e38aa3b, v110
	v_sub_f32_e32 v244, v193, v244
	v_mul_f32_e32 v111, 0x3e38aa3b, v111
	v_max3_f32 v215, v215, v104, v105
	v_xor_b32_e32 v241, 32, v207
	v_add_u32_e32 v245, 64, v245
	v_cndmask_b32_e64 v108, v210, v108, s[64:65]
	v_cndmask_b32_e64 v109, v210, v109, s[66:67]
	v_fma_f32 v110, v198, |v243|, v110
	v_fma_f32 v111, v198, |v244|, v111
	v_max3_f32 v215, v215, v106, v107
	v_cmp_lt_i32_e32 vcc, v241, v245
	v_cndmask_b32_e64 v110, v210, v110, s[68:69]
	v_cndmask_b32_e64 v111, v210, v111, s[70:71]
	v_max3_f32 v215, v215, v108, v109
	v_cndmask_b32_e32 v241, v207, v241, vcc
	v_max3_f32 v215, v215, v110, v111
	v_lshlrev_b32_e32 v241, 2, v241
	ds_bpermute_b32 v245, v241, v215
	s_waitcnt lgkmcnt(0)
	v_max_f32_e32 v245, v245, v245
	v_max_f32_e32 v215, v215, v245
	v_add_f32_e32 v245, 0x41000000, v180
	v_cmp_gt_f32_e32 vcc, v215, v245
	s_cbranch_vccz .LBB0_239
	v_max_f32_e32 v215, v215, v215
	v_max_f32_e32 v245, v180, v180
	v_max_f32_e32 v215, v245, v215
	v_sub_f32_e32 v180, v180, v215
	v_exp_f32_e32 v180, v180
	s_nop 0
	v_mul_f32_e32 v194, v194, v180
	v_pk_mul_f32 v[62:63], v[62:63], v[180:181] op_sel_hi:[1,0]
	v_pk_mul_f32 v[60:61], v[60:61], v[180:181] op_sel_hi:[1,0]
	v_pk_mul_f32 v[58:59], v[58:59], v[180:181] op_sel_hi:[1,0]
	v_pk_mul_f32 v[56:57], v[56:57], v[180:181] op_sel_hi:[1,0]
	v_pk_mul_f32 v[54:55], v[54:55], v[180:181] op_sel_hi:[1,0]
	v_pk_mul_f32 v[52:53], v[52:53], v[180:181] op_sel_hi:[1,0]
	v_pk_mul_f32 v[50:51], v[50:51], v[180:181] op_sel_hi:[1,0]
	v_pk_mul_f32 v[48:49], v[48:49], v[180:181] op_sel_hi:[1,0]
	v_pk_mul_f32 v[46:47], v[46:47], v[180:181] op_sel_hi:[1,0]
	v_pk_mul_f32 v[44:45], v[44:45], v[180:181] op_sel_hi:[1,0]
	v_pk_mul_f32 v[42:43], v[42:43], v[180:181] op_sel_hi:[1,0]
	v_pk_mul_f32 v[40:41], v[40:41], v[180:181] op_sel_hi:[1,0]
	v_pk_mul_f32 v[38:39], v[38:39], v[180:181] op_sel_hi:[1,0]
	v_pk_mul_f32 v[36:37], v[36:37], v[180:181] op_sel_hi:[1,0]
	v_pk_mul_f32 v[34:35], v[34:35], v[180:181] op_sel_hi:[1,0]
	v_pk_mul_f32 v[32:33], v[32:33], v[180:181] op_sel_hi:[1,0]
	v_mov_b32_e32 v180, v215

.LBB0_241:
	v_sub_f32_e32 v64, v112, v180
	v_sub_f32_e32 v65, v113, v180
	v_exp_f32_e32 v64, v64
	v_exp_f32_e32 v65, v65
	v_sub_f32_e32 v66, v114, v180
	v_exp_f32_e32 v66, v66
	v_sub_f32_e32 v67, v115, v180
	v_exp_f32_e32 v67, v67
	v_sub_f32_e32 v68, v116, v180
	v_exp_f32_e32 v72, v68
	v_sub_f32_e32 v68, v117, v180
	v_cvt_pk_bf16_f32 v76, v64, v65
	v_add_f32_e32 v64, 0, v64
	v_exp_f32_e32 v73, v68
	v_sub_f32_e32 v68, v118, v180
	v_add_f32_e32 v64, v65, v64
	v_exp_f32_e32 v74, v68
	v_sub_f32_e32 v68, v119, v180
	v_add_f32_e32 v64, v66, v64
	v_exp_f32_e32 v75, v68
	v_sub_f32_e32 v68, v120, v180
	v_add_f32_e32 v64, v67, v64
	v_exp_f32_e32 v112, v68
	v_sub_f32_e32 v68, v121, v180
	v_add_f32_e32 v64, v72, v64
	v_exp_f32_e32 v113, v68
	v_sub_f32_e32 v68, v122, v180
	v_add_f32_e32 v64, v73, v64
	v_exp_f32_e32 v114, v68
	v_sub_f32_e32 v68, v123, v180
	v_add_f32_e32 v64, v74, v64
	v_exp_f32_e32 v115, v68
	v_sub_f32_e32 v68, v124, v180
	v_add_f32_e32 v64, v75, v64
	v_exp_f32_e32 v116, v68
	v_sub_f32_e32 v68, v125, v180
	v_add_f32_e32 v64, v112, v64
	v_exp_f32_e32 v117, v68
	v_sub_f32_e32 v68, v126, v180
	v_add_f32_e32 v64, v113, v64
	v_exp_f32_e32 v118, v68
	v_sub_f32_e32 v68, v127, v180
	v_add_f32_e32 v64, v114, v64
	v_exp_f32_e32 v119, v68
	v_add_f32_e32 v64, v115, v64
	v_add_f32_e32 v64, v116, v64
	v_add_f32_e32 v64, v117, v64
	v_add_f32_e32 v64, v118, v64
	v_cvt_pk_bf16_f32 v68, v112, v113
	v_add_f32_e32 v112, v119, v64
	v_sub_f32_e32 v64, v96, v180
	v_exp_f32_e32 v96, v64
	v_sub_f32_e32 v64, v97, v180
	v_exp_f32_e32 v97, v64
	v_sub_f32_e32 v64, v98, v180
	v_exp_f32_e32 v98, v64
	v_sub_f32_e32 v64, v99, v180
	v_exp_f32_e32 v99, v64
	v_sub_f32_e32 v64, v100, v180
	v_cvt_pk_bf16_f32 v78, v72, v73
	v_exp_f32_e32 v100, v64
	v_sub_f32_e32 v64, v101, v180
	v_cvt_pk_bf16_f32 v72, v96, v97
	v_add_f32_e32 v96, v96, v112
	v_exp_f32_e32 v101, v64
	v_sub_f32_e32 v64, v102, v180
	v_add_f32_e32 v96, v97, v96
	v_exp_f32_e32 v102, v64
	v_sub_f32_e32 v64, v103, v180
	v_add_f32_e32 v96, v98, v96
	v_exp_f32_e32 v103, v64
	v_sub_f32_e32 v64, v104, v180
	v_add_f32_e32 v96, v99, v96
	v_exp_f32_e32 v104, v64
	v_sub_f32_e32 v64, v105, v180
	v_add_f32_e32 v96, v100, v96
	v_exp_f32_e32 v105, v64
	v_sub_f32_e32 v64, v106, v180
	v_add_f32_e32 v96, v101, v96
	v_exp_f32_e32 v106, v64
	v_sub_f32_e32 v64, v107, v180
	v_add_f32_e32 v96, v102, v96
	v_exp_f32_e32 v107, v64
	v_sub_f32_e32 v64, v108, v180
	v_add_f32_e32 v96, v103, v96
	v_exp_f32_e32 v108, v64
	v_sub_f32_e32 v64, v109, v180
	v_add_f32_e32 v96, v104, v96
	v_exp_f32_e32 v109, v64
	v_sub_f32_e32 v64, v110, v180
	v_add_f32_e32 v96, v105, v96
	v_exp_f32_e32 v110, v64
	v_add_f32_e32 v96, v106, v96
	v_add_f32_e32 v96, v107, v96
	v_add_f32_e32 v96, v108, v96
	v_add_f32_e32 v96, v109, v96
	v_add_f32_e32 v112, v110, v96
	v_sub_f32_e32 v96, v223, v181
	v_cvt_pk_bf16_f32 v69, v114, v115
	v_sub_f32_e32 v64, v111, v180
	v_exp_f32_e32 v114, v96
	v_sub_f32_e32 v96, v224, v181
	v_exp_f32_e32 v113, v64
	v_exp_f32_e32 v115, v96
	v_sub_f32_e32 v96, v225, v181
	v_cvt_pk_bf16_f32 v79, v74, v75
	v_cvt_pk_bf16_f32 v70, v116, v117
	v_cvt_pk_bf16_f32 v73, v98, v99
	v_cvt_pk_bf16_f32 v74, v100, v101
	v_exp_f32_e32 v116, v96
	v_sub_f32_e32 v100, v226, v181
	ds_read_b128 v[96:99], v184 offset:9216
	v_exp_f32_e32 v117, v100
	v_sub_f32_e32 v100, v219, v181
	v_cvt_pk_bf16_f32 v71, v118, v119
	v_exp_f32_e32 v118, v100
	v_sub_f32_e32 v100, v220, v181
	v_cvt_pk_bf16_f32 v77, v66, v67
	v_cvt_pk_bf16_f32 v64, v104, v105
	v_cvt_pk_bf16_f32 v66, v108, v109
	v_cvt_pk_bf16_f32 v67, v110, v113
	v_exp_f32_e32 v119, v100
	v_sub_f32_e32 v100, v222, v181
	v_sub_f32_e32 v104, v221, v181
	ds_read_b128 v[108:111], v184 offset:13824
	v_exp_f32_e32 v120, v100
	v_exp_f32_e32 v121, v104
	v_cvt_pk_bf16_f32 v65, v106, v107
	v_cvt_pk_bf16_f32 v104, v114, v115
	v_cvt_pk_bf16_f32 v105, v116, v117
	v_cvt_pk_bf16_f32 v106, v118, v119
	v_cvt_pk_bf16_f32 v107, v120, v121
	v_cvt_pk_bf16_f32 v75, v102, v103
	ds_read_b128 v[100:103], v184 offset:9248
	s_waitcnt lgkmcnt(2)
	v_mfma_f32_32x32x16_bf16 v[48:63], v[96:99], v[76:79], v[48:63]
	v_sub_f32_e32 v89, v89, v181
	v_sub_f32_e32 v88, v88, v181
	v_readlane_b32 s44, v255, 27
	v_readlane_b32 s45, v255, 28
	v_readlane_b32 s46, v255, 29
	v_readlane_b32 s47, v255, 30
	v_readlane_b32 s48, v255, 31
	v_mfma_f32_32x32x16_bf16 v[0:15], v[96:99], v[104:107], v[0:15]
	v_add_f32_e32 v96, v113, v112
	v_add_f32_e32 v194, v194, v96
	v_sub_f32_e32 v96, v203, v181
	v_exp_f32_e32 v112, v96
	v_sub_f32_e32 v96, v217, v181
	v_exp_f32_e32 v113, v96
	ds_read_b128 v[96:99], v184 offset:13856
	s_waitcnt lgkmcnt(2)
	v_mfma_f32_32x32x16_bf16 v[32:47], v[108:111], v[76:79], v[32:47]
	v_sub_f32_e32 v76, v185, v181
	v_exp_f32_e32 v122, v76
	v_sub_f32_e32 v76, v201, v181
	v_exp_f32_e32 v123, v76
	v_sub_f32_e32 v76, v202, v181
	v_exp_f32_e32 v124, v76
	v_sub_f32_e32 v76, v215, v181
	v_mfma_f32_32x32x16_bf16 v[16:31], v[108:111], v[104:107], v[16:31]
	v_exp_f32_e32 v104, v76
	v_sub_f32_e32 v76, v216, v181
	v_exp_f32_e32 v105, v76
	v_sub_f32_e32 v76, v218, v181
	v_exp_f32_e32 v106, v76
	v_add_f32_e32 v107, 0, v114
	v_add_f32_e32 v107, v115, v107
	v_cvt_pk_bf16_f32 v76, v112, v113
	v_cvt_pk_bf16_f32 v77, v122, v123
	s_waitcnt lgkmcnt(1)
	v_mfma_f32_32x32x16_bf16 v[48:63], v[100:103], v[68:71], v[48:63]
	v_cvt_pk_bf16_f32 v78, v124, v104
	v_cvt_pk_bf16_f32 v79, v105, v106
	v_add_f32_e32 v107, v116, v107
	v_add_f32_e32 v107, v117, v107
	v_add_f32_e32 v107, v118, v107
	v_readlane_b32 s49, v255, 32
	v_readlane_b32 s50, v255, 33
	s_waitcnt lgkmcnt(0)
	v_mfma_f32_32x32x16_bf16 v[32:47], v[96:99], v[68:71], v[32:47]
	v_sub_f32_e32 v68, v90, v181
	v_readlane_b32 s51, v255, 34
	v_mfma_f32_32x32x16_bf16 v[0:15], v[100:103], v[76:79], v[0:15]
	v_exp_f32_e32 v102, v68
	v_sub_f32_e32 v68, v91, v181
	v_exp_f32_e32 v103, v68
	v_sub_f32_e32 v68, v93, v181
	v_add_f32_e32 v100, v119, v107
	v_exp_f32_e32 v107, v68
	ds_read_b128 v[68:71], v184 offset:9280
	v_mfma_f32_32x32x16_bf16 v[16:31], v[96:99], v[76:79], v[16:31]
	v_sub_f32_e32 v76, v92, v181
	v_exp_f32_e32 v96, v76
	v_sub_f32_e32 v76, v94, v181
	v_exp_f32_e32 v97, v76
	v_sub_f32_e32 v76, v95, v181
	v_exp_f32_e32 v101, v89
	v_exp_f32_e32 v98, v76
	v_exp_f32_e32 v99, v88
	v_add_f32_e32 v100, v120, v100
	ds_read_b128 v[92:95], v184 offset:13888
	v_add_f32_e32 v100, v121, v100
	v_add_f32_e32 v100, v112, v100
	v_add_f32_e32 v100, v113, v100
	v_cvt_pk_bf16_f32 v88, v101, v102
	v_cvt_pk_bf16_f32 v89, v103, v107
	v_cvt_pk_bf16_f32 v90, v96, v97
	v_cvt_pk_bf16_f32 v91, v98, v99
	ds_read_b128 v[76:79], v184 offset:9312
	s_waitcnt lgkmcnt(2)
	v_mfma_f32_32x32x16_bf16 v[48:63], v[68:71], v[72:75], v[48:63]
	v_mfma_f32_32x32x16_bf16 v[0:15], v[68:71], v[88:91], v[0:15]
	v_add_f32_e32 v68, v122, v100
	v_add_f32_e32 v68, v123, v68
	v_add_f32_e32 v68, v124, v68
	v_add_f32_e32 v68, v104, v68
	v_add_f32_e32 v68, v105, v68
	v_add_f32_e32 v100, v106, v68
	ds_read_b128 v[68:71], v184 offset:13920
	s_waitcnt lgkmcnt(2)
	v_mfma_f32_32x32x16_bf16 v[32:47], v[92:95], v[72:75], v[32:47]
	v_sub_f32_e32 v72, v80, v181
	v_exp_f32_e32 v80, v72
	v_sub_f32_e32 v72, v81, v181
	v_exp_f32_e32 v81, v72
	v_sub_f32_e32 v72, v82, v181
	v_exp_f32_e32 v82, v72
	v_sub_f32_e32 v72, v83, v181
	v_exp_f32_e32 v83, v72
	v_sub_f32_e32 v72, v84, v181
	v_exp_f32_e32 v84, v72
	v_sub_f32_e32 v72, v85, v181
	v_exp_f32_e32 v85, v72
	v_sub_f32_e32 v72, v86, v181
	v_exp_f32_e32 v86, v72
	v_sub_f32_e32 v72, v87, v181
	v_exp_f32_e32 v87, v72
	v_mfma_f32_32x32x16_bf16 v[16:31], v[92:95], v[88:91], v[16:31]
	v_cvt_pk_bf16_f32 v72, v80, v81
	v_cvt_pk_bf16_f32 v73, v82, v83
	v_cvt_pk_bf16_f32 v74, v84, v85
	v_cvt_pk_bf16_f32 v75, v86, v87
	v_add_f32_e32 v88, v101, v100
	s_waitcnt lgkmcnt(1)
	v_mfma_f32_32x32x16_bf16 v[48:63], v[76:79], v[64:67], v[48:63]
	v_mfma_f32_32x32x16_bf16 v[0:15], v[76:79], v[72:75], v[0:15]
	v_add_f32_e32 v76, v102, v88
	v_add_f32_e32 v76, v103, v76
	v_add_f32_e32 v76, v107, v76
	v_add_f32_e32 v76, v96, v76
	v_add_f32_e32 v76, v97, v76
	v_add_f32_e32 v76, v98, v76
	v_add_f32_e32 v76, v99, v76
	s_waitcnt lgkmcnt(0)
	v_mfma_f32_32x32x16_bf16 v[32:47], v[68:71], v[64:67], v[32:47]
	v_add_f32_e32 v64, v80, v76
	v_add_f32_e32 v64, v81, v64
	v_add_f32_e32 v64, v82, v64
	v_add_f32_e32 v64, v83, v64
	v_add_f32_e32 v64, v84, v64
	v_add_f32_e32 v64, v85, v64
	v_add_f32_e32 v64, v86, v64
	v_mfma_f32_32x32x16_bf16 v[16:31], v[68:71], v[72:75], v[16:31]
	v_add_f32_e32 v64, v87, v64
	v_add_f32_e32 v173, v173, v64

.LBB0_243:
	s_add_i32 s75, s75, 1
	s_bitcmp1_b32 s75, 0
	s_cselect_b32 s0, 0x4900, 0
	s_add_i32 s0, s0, 0
	v_add_u32_e32 v64, s0, v187
	v_add_u32_e32 v65, v64, v174
	v_add3_u32 v64, v64, v190, v191
	s_waitcnt vmcnt(0)
	v_add_u32_e32 v64, 0x2000, v64
	ds_write_b128 v65, v[164:167]
	ds_write2_b64 v64, v[160:161], v[162:163] offset0:128 offset1:130
	s_and_saveexec_b64 s[6:7], s[4:5]
	s_cbranch_execz .LBB0_229
	v_add_u32_e32 v64, s0, v192
	ds_write_b32 v64, v175 offset:18432
	s_branch .LBB0_229
